# late GEMM tile: dead re-staging of the last k-tile in the peeled final iteration removed (loads, norm math, LDS writes)
# speedup vs baseline: 1.0041x; 1.0008x over previous
; __device__ __forceinline__ bf16_t f2bf(float f) { return (bf16_t)(pack2(f, 0.f) & 0xffffu); }
; __device__ __forceinline__ void gemm_late_tile(const Params& p, int l, int mt_, int nt_, unsigned char* smem) {
;     ...
;   L_LOAD(0);
;   L_STORE(0);
;   __syncthreads();
;   for (int kt = 0; kt < 16; ++kt) {
;     L_LOAD((kt + 1 < 16) ? kt + 1 : 15);
;     G_COMPUTE(kt & 1);
;     L_STORE((kt + 1) & 1);
;     __syncthreads();
;   }
;     ...
;         float v0 = acc[i][0][j], v1 = acc[i][1][j], v2 = acc[i][2][j], v3 = acc[i][3][j];
;         if (cbase < 512 && pp >= 256) {
;           const int tt = pp - 256, rp = tt >> 6, cp = tt & 63;
;           const float2 cs0 = *(const float2*)(p.rope + (rp * 16 + fr) * 2);
;           const float2 cs1 = *(const float2*)(p.rope + (cp * 16 + fr) * 2);
;           float n0_ = v0 * cs0.x - v1 * cs0.y, n1_ = v0 * cs0.y + v1 * cs0.x;
;           float n2_ = v2 * cs1.x - v3 * cs1.y, n3_ = v2 * cs1.y + v3 * cs1.x;
;           v0 = n0_; v1 = n1_; v2 = n2_; v3 = n3_;
;         }
;         if (cbase < 384) { v0 *= 0.125f; v1 *= 0.125f; v2 *= 0.125f; v3 *= 0.125f; }
;         bf16_t* o = wbuf + (i * 16 + fq * 4 + j) * 72 + fr;
;         o[0] = f2bf(v0); o[16] = f2bf(v1); o[32] = f2bf(v2); o[48] = f2bf(v3);
.Llate_nopf:
	s_waitcnt lgkmcnt(0)
	s_barrier
	s_cbranch_scc1 .LBB0_588
	s_nop 0
	s_nop 0
	s_nop 0
	s_nop 0
	s_nop 0
	s_nop 0
	s_nop 0
	s_nop 0
	v_add_co_u32_e32 v76, vcc, 0x30000, v120
	s_nop 0
	s_nop 0
	v_addc_co_u32_e32 v77, vcc, 0, v121, vcc
	s_nop 0
	ds_read_b128 v[80:83], v144 offset:18432
	ds_read_b128 v[84:87], v143 offset:55296
	ds_read_b128 v[90:93], v144 offset:20736
	ds_read_b128 v[130:133], v143 offset:57600
	ds_read_b128 v[134:137], v144 offset:23040
	ds_read_b128 v[146:149], v143 offset:59904
	ds_read_b128 v[150:153], v144 offset:25344
	ds_read_b128 v[154:157], v143 offset:62208
	s_mov_b64 s[0:1], 0x20f00
	s_waitcnt lgkmcnt(6)
	v_mfma_f32_16x16x32_bf16 v[60:63], v[80:83], v[84:87], v[60:63]
	s_nop 0
	s_mov_b64 s[0:1], 0x40f00
	s_nop 0
	s_waitcnt lgkmcnt(4)
	v_mfma_f32_16x16x32_bf16 v[56:59], v[80:83], v[130:133], v[56:59]
	s_mov_b64 s[0:1], 0x60f00
	s_nop 0
	s_mov_b64 s[0:1], 0x1f00
	s_waitcnt lgkmcnt(2)
	v_mfma_f32_16x16x32_bf16 v[52:55], v[80:83], v[146:149], v[52:55]
	s_nop 0
	s_cmp_lt_i32 s55, 0
	s_movk_i32 s0, 0xfc00
	s_waitcnt lgkmcnt(0)
	v_mfma_f32_16x16x32_bf16 v[48:51], v[80:83], v[154:157], v[48:51]
	s_cselect_b32 s48, s0, 0xfffff800
	v_readlane_b32 s0, v251, 48
	v_lshrrev_b32_e32 v128, 6, v105
	v_mfma_f32_16x16x32_bf16 v[44:47], v[90:93], v[84:87], v[44:47]
	s_movk_i32 s0, 0x2400
	v_readlane_b32 s10, v251, 58
	v_readlane_b32 s12, v251, 60
	v_mfma_f32_16x16x32_bf16 v[40:43], v[90:93], v[130:133], v[40:43]
	v_readlane_b32 s11, v251, 59
	v_readlane_b32 s13, v251, 61
	s_cselect_b32 s50, s10, s12
	v_mfma_f32_16x16x32_bf16 v[36:39], v[90:93], v[146:149], v[36:39]
	s_cselect_b32 s49, s11, s13
	v_readlane_b32 s1, v251, 49
	v_readlane_b32 s2, v251, 50
	v_mfma_f32_16x16x32_bf16 v[32:35], v[90:93], v[154:157], v[32:35]
	v_readlane_b32 s3, v251, 51
	v_readlane_b32 s4, v251, 52
	v_readlane_b32 s5, v251, 53
	v_mfma_f32_16x16x32_bf16 v[28:31], v[134:137], v[84:87], v[28:31]
	v_readlane_b32 s6, v251, 54
	v_readlane_b32 s7, v251, 55
	v_readlane_b32 s8, v251, 56
	v_mfma_f32_16x16x32_bf16 v[24:27], v[134:137], v[130:133], v[24:27]
	v_readlane_b32 s9, v251, 57
	v_readlane_b32 s14, v251, 62
	v_readlane_b32 s15, v251, 63
	v_mfma_f32_16x16x32_bf16 v[20:23], v[134:137], v[146:149], v[20:23]
	v_mfma_f32_16x16x32_bf16 v[16:19], v[134:137], v[154:157], v[16:19]
	v_mfma_f32_16x16x32_bf16 v[12:15], v[150:153], v[84:87], v[12:15]
	v_mfma_f32_16x16x32_bf16 v[8:11], v[150:153], v[130:133], v[8:11]
	v_mfma_f32_16x16x32_bf16 v[4:7], v[150:153], v[146:149], v[4:7]
	v_mfma_f32_16x16x32_bf16 v[0:3], v[150:153], v[154:157], v[0:3]
	ds_read_b128 v[80:83], v144 offset:18496
	ds_read_b128 v[84:87], v143 offset:55360
	ds_read_b128 v[90:93], v144 offset:20800
	ds_read_b128 v[130:133], v143 offset:57664
	ds_read_b128 v[134:137], v144 offset:23104
	ds_read_b128 v[146:149], v143 offset:59968
	ds_read_b128 v[150:153], v144 offset:25408
	ds_read_b128 v[154:157], v143 offset:62272
	s_waitcnt lgkmcnt(6)
	v_mfma_f32_16x16x32_bf16 v[60:63], v[80:83], v[84:87], v[60:63]
	s_waitcnt lgkmcnt(4)
	v_mfma_f32_16x16x32_bf16 v[56:59], v[80:83], v[130:133], v[56:59]
	s_waitcnt lgkmcnt(2)
	v_mfma_f32_16x16x32_bf16 v[52:55], v[80:83], v[146:149], v[52:55]
	s_nop 3
	v_cvt_pk_bf16_f32 v60, v60, s0
	s_nop 0
	v_cvt_pk_bf16_f32 v56, v56, s0
	s_waitcnt lgkmcnt(0)
	v_mfma_f32_16x16x32_bf16 v[48:51], v[80:83], v[154:157], v[48:51]
	v_mfma_f32_16x16x32_bf16 v[44:47], v[90:93], v[84:87], v[44:47]
	v_cvt_pk_bf16_f32 v52, v52, s0
	s_nop 5
	v_cvt_pk_bf16_f32 v48, v48, s0
	v_mfma_f32_16x16x32_bf16 v[40:43], v[90:93], v[130:133], v[40:43]
	v_mfma_f32_16x16x32_bf16 v[36:39], v[90:93], v[146:149], v[36:39]
	v_cvt_pk_bf16_f32 v44, v44, s0
	s_nop 5
	v_cvt_pk_bf16_f32 v40, v40, s0
	v_mfma_f32_16x16x32_bf16 v[32:35], v[90:93], v[154:157], v[32:35]
	v_mfma_f32_16x16x32_bf16 v[28:31], v[134:137], v[84:87], v[28:31]
	v_cvt_pk_bf16_f32 v36, v36, s0
	s_nop 5
	v_cvt_pk_bf16_f32 v32, v32, s0
	v_mfma_f32_16x16x32_bf16 v[24:27], v[134:137], v[130:133], v[24:27]
	v_mfma_f32_16x16x32_bf16 v[20:23], v[134:137], v[146:149], v[20:23]
	v_cvt_pk_bf16_f32 v28, v28, s0
	s_nop 5
	v_cvt_pk_bf16_f32 v24, v24, s0
	v_mfma_f32_16x16x32_bf16 v[16:19], v[134:137], v[154:157], v[16:19]
	v_mfma_f32_16x16x32_bf16 v[12:15], v[150:153], v[84:87], v[12:15]
	v_cvt_pk_bf16_f32 v20, v20, s0
	s_nop 5
	v_cvt_pk_bf16_f32 v16, v16, s0
	v_mfma_f32_16x16x32_bf16 v[8:11], v[150:153], v[130:133], v[8:11]
	v_mfma_f32_16x16x32_bf16 v[4:7], v[150:153], v[146:149], v[4:7]
	s_nop 0
	s_nop 0
	s_nop 0
	s_nop 0
	s_nop 0
	s_nop 0
	s_nop 0
	s_nop 0
	s_nop 0
	s_nop 0
	v_cvt_pk_bf16_f32 v12, v12, s0
	v_cvt_pk_bf16_f32 v8, v8, s0
	v_mfma_f32_16x16x32_bf16 v[0:3], v[150:153], v[154:157], v[0:3]
	v_cvt_pk_bf16_f32 v4, v4, s0
	s_waitcnt vmcnt(6)
	s_nop 0
	s_nop 4
	v_cvt_pk_bf16_f32 v0, v0, s0
	s_waitcnt vmcnt(4)
	s_nop 0
	s_waitcnt vmcnt(3)
	s_nop 0
	s_nop 0
	s_waitcnt vmcnt(2)
	s_nop 0
	s_waitcnt vmcnt(0)
	s_nop 0
	s_nop 0
	s_nop 0
	s_nop 0
	s_nop 0
	s_nop 0
	s_nop 0
	s_nop 0
	s_nop 0
	s_nop 0
	s_nop 0
	s_nop 0
	s_nop 0
	s_nop 0
	s_nop 0
	s_nop 0
	s_nop 0
	s_nop 0
	s_nop 0
	s_nop 0
	s_nop 0
	s_waitcnt vmcnt(1)
	s_nop 0
	s_nop 0
	s_nop 0
	s_nop 0
	s_nop 0
	s_nop 0
	s_nop 0
	s_nop 0
	s_waitcnt vmcnt(0)
	s_nop 0
	s_nop 0
	s_nop 0
	s_nop 0
	s_nop 0
	s_nop 0
	s_nop 0
	s_nop 0
	s_nop 0
	s_nop 0
	s_nop 0
	s_nop 0
	s_waitcnt vmcnt(1)
	s_nop 0
	s_nop 0
	s_nop 0
	s_nop 0
	s_nop 0
	s_nop 0
	s_nop 0
	s_nop 0
	s_waitcnt vmcnt(0)
	s_nop 0
	s_nop 0
	s_nop 0
	s_nop 0
	s_nop 0
	s_nop 0
	s_nop 0
	s_nop 0
	s_nop 0
	s_nop 0
	s_nop 0
	s_waitcnt vmcnt(1)
	s_nop 0
	s_nop 0
	s_nop 0
	s_nop 0
	s_nop 0
	s_nop 0
	s_nop 0
	s_nop 0
	s_nop 0
	s_nop 0
	s_nop 0
	s_nop 0
	s_waitcnt vmcnt(0)
	s_nop 0
	s_nop 0
	s_nop 0
	s_nop 0
	s_nop 0
	s_nop 0
	s_nop 0
	s_nop 0
	s_nop 0
	s_nop 0
	s_nop 0
	s_nop 0
	s_nop 0
	s_nop 0
	s_nop 0
	s_nop 0
	s_nop 0
	s_nop 0
	s_nop 0
	v_mul_lo_u32 v66, v128, s0
	v_add_u32_e32 v66, 0, v66
	v_lshlrev_b32_e32 v67, 1, v139
	v_mul_u32_u24_e32 v68, 0x240, v140
	v_add3_u32 v67, v66, v67, v68
	s_waitcnt lgkmcnt(0)
	s_barrier
; __device__ __forceinline__ void gemm_late_tile(const Params& p, int l, int mt_, int nt_, unsigned char* smem) {
;     ...
;     __builtin_amdgcn_wave_barrier();
;     {
;       const int ch = lane & 7;
;       const bool chv = (cbase + ch * 8) < 3600;
;       const bool halo = (cbase >= 2688) && (cbase + 64 <= 3584);
; #pragma unroll
;       for (int t = 0; t < 8; ++t) {
;         const int rl = (lane >> 3) + 8 * t;
;         const uint4 v = *(const uint4*)(wbuf + rl * 72 + ch * 8);
;         const int r = m0 + wr * 64 + rl;
;         if (chv) *(uint4*)(dst + (size_t)r * ld + coff + ch * 8) = v;
;         if (halo) {
;           const int pp = r % TPB, q34 = pp % 34, t34 = pp / 34, bb = r / TPB;
;           if (q34 == 33 && t34 + 1 < 128) *(uint4*)(p.HALO + ((size_t)(bb * 128 + t34 + 1) * 2 + 0) * 896 + coff + ch * 8) = v;
;           if (q34 == 0 && t34 >= 1) *(uint4*)(p.HALO + ((size_t)(bb * 128 + t34 - 1) * 2 + 1) * 896 + coff + ch * 8) = v;
;         }
;       }
;     }
;   __syncthreads();
	ds_write_b16 v67, v48 offset:96
	v_cvt_pk_bf16_f32 v48, v61, s0
	ds_write_b16 v67, v32 offset:2400
	v_cvt_pk_bf16_f32 v32, v45, s0
	ds_write_b16 v67, v16 offset:4704
	v_cvt_pk_bf16_f32 v16, v29, s0
	ds_write_b16 v67, v0 offset:7008
	v_cvt_pk_bf16_f32 v0, v13, s0
	ds_write_b16 v67, v48 offset:144
	v_cvt_pk_bf16_f32 v48, v57, s0
	ds_write_b16 v67, v32 offset:2448
	v_cvt_pk_bf16_f32 v32, v41, s0
	ds_write_b16 v67, v16 offset:4752
	v_cvt_pk_bf16_f32 v16, v25, s0
	ds_write_b16 v67, v0 offset:7056
	v_cvt_pk_bf16_f32 v0, v9, s0
	ds_write_b16 v67, v48 offset:176
	v_cvt_pk_bf16_f32 v48, v53, s0
	ds_write_b16 v67, v32 offset:2480
	v_cvt_pk_bf16_f32 v32, v37, s0
	ds_write_b16 v67, v16 offset:4784
	v_cvt_pk_bf16_f32 v16, v21, s0
	ds_write_b16 v67, v0 offset:7088
	v_cvt_pk_bf16_f32 v0, v5, s0
	ds_write_b16 v67, v48 offset:208
	v_cvt_pk_bf16_f32 v48, v49, s0
	ds_write_b16 v67, v32 offset:2512
	v_cvt_pk_bf16_f32 v32, v33, s0
	ds_write_b16 v67, v16 offset:4816
	v_cvt_pk_bf16_f32 v16, v17, s0
	ds_write_b16 v67, v0 offset:7120
	v_cvt_pk_bf16_f32 v0, v1, s0
	ds_write_b16 v67, v48 offset:240
	v_cvt_pk_bf16_f32 v48, v62, s0
	ds_write_b16 v67, v32 offset:2544
	v_cvt_pk_bf16_f32 v32, v46, s0
	ds_write_b16 v67, v16 offset:4848
	v_cvt_pk_bf16_f32 v16, v30, s0
	ds_write_b16 v67, v0 offset:7152
	v_cvt_pk_bf16_f32 v0, v14, s0
	ds_write_b16 v67, v48 offset:288
	v_cvt_pk_bf16_f32 v48, v58, s0
	ds_write_b16 v67, v32 offset:2592
	v_cvt_pk_bf16_f32 v32, v42, s0
	ds_write_b16 v67, v16 offset:4896
	v_cvt_pk_bf16_f32 v16, v26, s0
	ds_write_b16 v67, v0 offset:7200
	v_cvt_pk_bf16_f32 v0, v10, s0
	ds_write_b16 v67, v48 offset:320
	v_cvt_pk_bf16_f32 v48, v54, s0
	ds_write_b16 v67, v32 offset:2624
	v_cvt_pk_bf16_f32 v32, v38, s0
	ds_write_b16 v67, v16 offset:4928
	v_cvt_pk_bf16_f32 v16, v22, s0
	ds_write_b16 v67, v0 offset:7232
	v_cvt_pk_bf16_f32 v0, v6, s0
	ds_write_b16 v67, v48 offset:352
	v_cvt_pk_bf16_f32 v48, v50, s0
	ds_write_b16 v67, v32 offset:2656
	v_cvt_pk_bf16_f32 v32, v34, s0
	ds_write_b16 v67, v16 offset:4960
	v_cvt_pk_bf16_f32 v16, v18, s0
	ds_write_b16 v67, v0 offset:7264
	v_cvt_pk_bf16_f32 v0, v2, s0
	ds_write_b16 v67, v48 offset:384
	v_cvt_pk_bf16_f32 v48, v63, s0
	ds_write_b16 v67, v32 offset:2688
	v_cvt_pk_bf16_f32 v32, v47, s0
	ds_write_b16 v67, v16 offset:4992
	v_cvt_pk_bf16_f32 v16, v31, s0
	ds_write_b16 v67, v0 offset:7296
	v_cvt_pk_bf16_f32 v0, v15, s0
	ds_write_b16 v67, v48 offset:432
	v_cvt_pk_bf16_f32 v48, v59, s0
	ds_write_b16 v67, v32 offset:2736
	v_cvt_pk_bf16_f32 v32, v43, s0
	ds_write_b16 v67, v16 offset:5040
	v_cvt_pk_bf16_f32 v16, v27, s0
	ds_write_b16 v67, v0 offset:7344
	v_cvt_pk_bf16_f32 v0, v11, s0
	ds_write_b16 v67, v48 offset:464
	v_cvt_pk_bf16_f32 v48, v55, s0
	ds_write_b16 v67, v32 offset:2768
	v_cvt_pk_bf16_f32 v32, v39, s0
	ds_write_b16 v67, v16 offset:5072
	v_cvt_pk_bf16_f32 v16, v23, s0
	ds_write_b16 v67, v0 offset:7376
	v_cvt_pk_bf16_f32 v0, v7, s0
	ds_write_b16 v67, v48 offset:496
	v_cvt_pk_bf16_f32 v48, v51, s0
	ds_write_b16 v67, v32 offset:2800
	v_cvt_pk_bf16_f32 v32, v35, s0
	ds_write_b16 v67, v16 offset:5104
	v_cvt_pk_bf16_f32 v16, v19, s0
	ds_write_b16 v67, v0 offset:7408
	v_cvt_pk_bf16_f32 v0, v3, s0
	s_movk_i32 s0, 0x400
	v_mov_b32_e32 v64, s50
	s_cselect_b32 s50, s0, 0x280
	s_add_i32 s48, s48, s54
	v_mov_b32_e32 v65, s49
	ds_write_b16 v67, v0 offset:7440
	v_and_or_b32 v0, v105, 64, s48
	v_mov_b32_e32 v1, v164
	v_lshrrev_b32_e32 v7, 3, v138
	v_lshlrev_b32_e32 v2, 1, v104
	v_lshl_add_u64 v[0:1], v[0:1], 1, v[64:65]
	v_mov_b32_e32 v3, v164
	ds_write_b16 v67, v4 offset:6976
	v_lshl_add_u64 v[4:5], v[0:1], 0, v[2:3]
	v_mul_u32_u24_e32 v0, 0x90, v7
	v_add3_u32 v9, v66, v2, v0
	ds_write_b16 v67, v60
	ds_write_b16 v67, v56 offset:32
	ds_write_b16 v67, v52 offset:64
	ds_write_b16 v67, v48 offset:528
	ds_write_b16 v67, v44 offset:2304
	ds_write_b16 v67, v40 offset:2336
	ds_write_b16 v67, v36 offset:2368
	ds_write_b16 v67, v32 offset:2832
	ds_write_b16 v67, v28 offset:4608
	ds_write_b16 v67, v24 offset:4640
	ds_write_b16 v67, v20 offset:4672
	ds_write_b16 v67, v16 offset:5136
	ds_write_b16 v67, v12 offset:6912
	ds_write_b16 v67, v8 offset:6944
	ds_read_b128 v[0:3], v9
	v_add_u32_e32 v6, s28, v142
	v_or_b32_e32 v8, v6, v7
	v_mad_i64_i32 v[6:7], s[48:49], s50, v8, 0
	v_lshl_add_u64 v[6:7], v[6:7], 1, v[4:5]
	s_waitcnt lgkmcnt(0)
	global_store_dwordx4 v[6:7], v[0:3], off
	ds_read_b128 v[0:3], v9 offset:1152
	v_or_b32_e32 v6, 8, v8
	v_mad_i64_i32 v[6:7], s[48:49], s50, v6, 0
	v_lshl_add_u64 v[6:7], v[6:7], 1, v[4:5]
	s_waitcnt lgkmcnt(0)
	global_store_dwordx4 v[6:7], v[0:3], off
	ds_read_b128 v[0:3], v9 offset:2304
	v_or_b32_e32 v6, 16, v8
	v_mad_i64_i32 v[6:7], s[48:49], s50, v6, 0
	v_lshl_add_u64 v[6:7], v[6:7], 1, v[4:5]
	s_waitcnt lgkmcnt(0)
	global_store_dwordx4 v[6:7], v[0:3], off
	ds_read_b128 v[0:3], v9 offset:3456
	v_or_b32_e32 v6, 24, v8
	v_mad_i64_i32 v[6:7], s[48:49], s50, v6, 0
	v_lshl_add_u64 v[6:7], v[6:7], 1, v[4:5]
	s_waitcnt lgkmcnt(0)
	global_store_dwordx4 v[6:7], v[0:3], off
	ds_read_b128 v[0:3], v9 offset:4608
	v_or_b32_e32 v6, 32, v8
	v_mad_i64_i32 v[6:7], s[48:49], s50, v6, 0
	v_lshl_add_u64 v[6:7], v[6:7], 1, v[4:5]
	s_waitcnt lgkmcnt(0)
	global_store_dwordx4 v[6:7], v[0:3], off
	ds_read_b128 v[0:3], v9 offset:5760
	v_or_b32_e32 v6, 40, v8
	v_mad_i64_i32 v[6:7], s[48:49], s50, v6, 0
	v_lshl_add_u64 v[6:7], v[6:7], 1, v[4:5]
	s_waitcnt lgkmcnt(0)
	global_store_dwordx4 v[6:7], v[0:3], off
	ds_read_b128 v[0:3], v9 offset:6912
	v_or_b32_e32 v6, 48, v8
	v_mad_i64_i32 v[6:7], s[48:49], s50, v6, 0
	v_lshl_add_u64 v[6:7], v[6:7], 1, v[4:5]
	s_waitcnt lgkmcnt(0)
	global_store_dwordx4 v[6:7], v[0:3], off
	ds_read_b128 v[0:3], v9 offset:8064
	v_or_b32_e32 v6, 56, v8
	v_mad_i64_i32 v[6:7], s[48:49], s50, v6, 0
	v_lshl_add_u64 v[4:5], v[6:7], 1, v[4:5]
	s_mov_b64 s[48:49], 0
	s_waitcnt lgkmcnt(0)
	global_store_dwordx4 v[4:5], v[0:3], off
	s_barrier
	s_branch .LBB0_570
